# EpiRes GEMM: vmcnt(0) hoisted out of K loop; GUP unit-top store drain removed; attention K tiles prefetched one block ahead
# speedup vs baseline: 1.0299x; 1.0023x over previous
;     DI bool next(int i, Unit& u) const { if (i > 0 || c >= 44) return false; u.pm = 128 + c / 22; u.pn = c % 22; u.k0 = 0; u.np = 8; return true; }
; #define PG8_BAR __builtin_amdgcn_s_barrier()
; template <class Epi, class Sched>
; DI void gemm_phase(LAS unsigned char* lds, const Gemm g, const Sched& S, const Epi& E, const int tid) {
;     ...
;     for (;;) {
;         const bool has_next = S.next(ui + 1, nxt);
;         const char* nA = has_next ? (const char*)g.A + (size_t)nxt.pm * tstepA + (size_t)nxt.pn * g.acol * 2 + (size_t)nxt.k0 * 256 : cA; const char* nB = has_next ? (const char*)g.Bt + (size_t)nxt.pn * tstepB + (size_t)nxt.k0 * 256 : cB;
;         const int nt = 2 * cur.np;
;     ...
; #pragma unroll
;         for (int a = 0; a < 2; ++a)
; #pragma unroll
;             for (int b = 0; b < 2; ++b)
; #pragma unroll
;                 for (int m = 0; m < 4; ++m)
; #pragma unroll
;                     for (int n = 0; n < 2; ++n) acc[a][b][m][n] = (f32x4){0.f, 0.f, 0.f, 0.f};
;         cur = nxt; cA = nA; cB = nB; ++ui;
;         if (wr == 1) PG8_BAR;
.LBB0_84:
	s_ashr_i32 s27, s26, 31
	s_lshl_b64 s[10:11], s[26:27], 19
	s_add_u32 s28, s76, s10
	s_addc_u32 s29, s82, s11
	s_and_b64 s[10:11], s[46:47], exec
	s_cselect_b32 s1, s29, s7
	s_cselect_b32 s10, s28, s6
	s_ashr_i32 s53, s52, 31
	s_lshl_b64 s[30:31], s[52:53], 19
	s_add_u32 s50, s12, s30
	s_addc_u32 s51, s13, s31
	s_and_b64 s[30:31], s[46:47], exec
	s_cselect_b32 s11, s51, s5
	s_cselect_b32 s27, s50, s4
	s_add_u32 s49, s4, 0x100
	s_addc_u32 s53, s5, 0
	s_add_u32 s30, s6, 0x40080
	v_mov_b32_e32 v0, 0
	s_addc_u32 s31, s7, 0
	s_mov_b32 vcc_lo, -2
	v_mov_b32_e32 v1, v0
	v_mov_b32_e32 v2, v0
	v_mov_b32_e32 v3, v0
	v_mov_b32_e32 v4, v0
	v_mov_b32_e32 v5, v0
	v_mov_b32_e32 v6, v0
	v_mov_b32_e32 v7, v0
	s_waitcnt lgkmcnt(0)
	v_mov_b32_e32 v20, v0
	v_mov_b32_e32 v21, v0
	v_mov_b32_e32 v22, v0
	v_mov_b32_e32 v23, v0
	v_mov_b32_e32 v28, v0
	v_mov_b32_e32 v29, v0
	v_mov_b32_e32 v30, v0
	v_mov_b32_e32 v31, v0
	v_mov_b32_e32 v36, v0
	v_mov_b32_e32 v37, v0
	v_mov_b32_e32 v38, v0
	v_mov_b32_e32 v39, v0
	v_mov_b32_e32 v44, v0
	v_mov_b32_e32 v45, v0
	v_mov_b32_e32 v46, v0
	v_mov_b32_e32 v47, v0
	v_mov_b32_e32 v52, v0
	v_mov_b32_e32 v53, v0
	v_mov_b32_e32 v54, v0
	v_mov_b32_e32 v55, v0
	v_mov_b32_e32 v60, v0
	v_mov_b32_e32 v61, v0
	v_mov_b32_e32 v62, v0
	v_mov_b32_e32 v63, v0
	v_mov_b32_e32 v8, v0
	v_mov_b32_e32 v9, v0
	v_mov_b32_e32 v10, v0
	v_mov_b32_e32 v11, v0
	v_mov_b32_e32 v12, v0
	v_mov_b32_e32 v13, v0
	v_mov_b32_e32 v14, v0
	v_mov_b32_e32 v15, v0
	v_mov_b32_e32 v16, v0
	v_mov_b32_e32 v17, v0
	v_mov_b32_e32 v18, v0
	v_mov_b32_e32 v19, v0
	v_mov_b32_e32 v24, v0
	v_mov_b32_e32 v25, v0
	v_mov_b32_e32 v26, v0
	v_mov_b32_e32 v27, v0
	v_mov_b32_e32 v32, v0
	v_mov_b32_e32 v33, v0
	v_mov_b32_e32 v34, v0
	v_mov_b32_e32 v35, v0
	v_mov_b32_e32 v40, v0
	v_mov_b32_e32 v41, v0
	v_mov_b32_e32 v42, v0
	v_mov_b32_e32 v43, v0
	v_mov_b32_e32 v48, v0
	v_mov_b32_e32 v49, v0
	v_mov_b32_e32 v50, v0
	v_mov_b32_e32 v51, v0
	v_mov_b32_e32 v56, v0
	v_mov_b32_e32 v57, v0
	v_mov_b32_e32 v58, v0
	v_mov_b32_e32 v59, v0
	v_mov_b32_e32 v78, v0
	v_mov_b32_e32 v79, v0
	v_mov_b32_e32 v80, v0
	v_mov_b32_e32 v81, v0
	v_mov_b32_e32 v86, v0
	v_mov_b32_e32 v87, v0
	v_mov_b32_e32 v88, v0
	v_mov_b32_e32 v89, v0
	v_mov_b32_e32 v118, v0
	v_mov_b32_e32 v119, v0
	v_mov_b32_e32 v120, v0
	v_mov_b32_e32 v121, v0
	v_mov_b32_e32 v126, v0
	v_mov_b32_e32 v127, v0
	v_mov_b32_e32 v128, v0
	v_mov_b32_e32 v129, v0
	v_mov_b32_e32 v134, v0
	v_mov_b32_e32 v135, v0
	v_mov_b32_e32 v136, v0
	v_mov_b32_e32 v137, v0
	v_mov_b32_e32 v142, v0
	v_mov_b32_e32 v143, v0
	v_mov_b32_e32 v144, v0
	v_mov_b32_e32 v145, v0
	v_mov_b32_e32 v150, v0
	v_mov_b32_e32 v151, v0
	v_mov_b32_e32 v152, v0
	v_mov_b32_e32 v153, v0
	v_mov_b32_e32 v158, v0
	v_mov_b32_e32 v159, v0
	v_mov_b32_e32 v160, v0
	v_mov_b32_e32 v161, v0
	v_mov_b32_e32 v106, v0
	v_mov_b32_e32 v107, v0
	v_mov_b32_e32 v108, v0
	v_mov_b32_e32 v109, v0
	v_mov_b32_e32 v110, v0
	v_mov_b32_e32 v111, v0
	v_mov_b32_e32 v112, v0
	v_mov_b32_e32 v113, v0
	v_mov_b32_e32 v114, v0
	v_mov_b32_e32 v115, v0
	v_mov_b32_e32 v116, v0
	v_mov_b32_e32 v117, v0
	v_mov_b32_e32 v122, v0
	v_mov_b32_e32 v123, v0
	v_mov_b32_e32 v124, v0
	v_mov_b32_e32 v125, v0
	v_mov_b32_e32 v130, v0
	v_mov_b32_e32 v131, v0
	v_mov_b32_e32 v132, v0
	v_mov_b32_e32 v133, v0
	v_mov_b32_e32 v138, v0
	v_mov_b32_e32 v139, v0
	v_mov_b32_e32 v140, v0
	v_mov_b32_e32 v141, v0
	v_mov_b32_e32 v146, v0
	v_mov_b32_e32 v147, v0
	v_mov_b32_e32 v148, v0
	v_mov_b32_e32 v149, v0
	v_mov_b32_e32 v154, v0
	v_mov_b32_e32 v155, v0
	v_mov_b32_e32 v156, v0
	v_mov_b32_e32 v157, v0

; DI int crow(int r, int hi) { return (r & 3) + 8 * (r >> 2) + 4 * hi; }
; #define MFMA32(a, b, c) __builtin_amdgcn_mfma_f32_32x32x16_bf16((a), (b), (c), 0, 0, 0)
; DI void sb_attention(const Params& p, int gw, int NGW, int lane) {
;     ...
;             const int key0 = kb * 32; const bool diag = (kb == kb_start);
;             f32x16 c;
; #pragma unroll
;             for (int e = 0; e < 16; ++e) c[e] = 0.f;
; #pragma unroll
;             for (int d0 = 0; d0 < 4; ++d0) { const bf16x8 kf = *(const bf16x8*)(Kb + (size_t)(key0 + n31) * D + d0 * 16 + hi * 8); c = MFMA32(kf, qf[d0], c); }
;             u32x2 vlo[2][2], vhi[2][2];
; #pragma unroll
;             for (int s2 = 0; s2 < 2; ++s2)
; #pragma unroll
;                 for (int dblk = 0; dblk < 2; ++dblk) { const bf16_t* vp = VT + (size_t)(dblk * 32 + n31) * Lrow + key0 + 16 * s2 + 4 * hi; vlo[s2][dblk] = *(const u32x2*)vp; vhi[s2][dblk] = *(const u32x2*)(vp + 8); }
;             float sp[16], ls[16];
; #pragma unroll
;             for (int e = 0; e < 16; ++e) {
;                 const float z = c[e] * 0.125f; const float az = fabsf(z);
;                 const float l = __builtin_amdgcn_logf(1.f + __builtin_amdgcn_exp2f(-az * 1.4426950408889634f)) * 0.6931471805599453f;
;                 const bool valid = !diag || (crow(e, hi) < n31);
;                 sp[e] = valid ? fmaxf(z, 0.f) + l : 0.f; ls[e] = valid ? fminf(z, 0.f) - l : -1e30f;
;             }
.LBB0_349:
	v_lshl_add_u64 v[0:1], s[14:15], 0, v[82:83]
	v_lshlrev_b64 v[88:89], 11, v[0:1]
	v_mov_b32_e32 v87, v65
	v_or_b32_e32 v0, s11, v82
	v_lshl_add_u64 v[90:91], s[12:13], 0, v[86:87]
	v_lshlrev_b32_e32 v64, 11, v0
	v_lshl_add_u64 v[4:5], v[90:91], 0, v[64:65]
	global_load_dwordx4 v[0:3], v[4:5], off
	v_lshl_add_u64 v[6:7], s[0:1], 0, v[88:89]
	v_lshl_add_u64 v[6:7], s[30:31], 1, v[6:7]
	v_lshl_add_u64 v[28:29], v[6:7], 0, v[86:87]
	global_load_dwordx4 v[48:51], v[28:29], off
	global_load_dwordx4 v[16:19], v[4:5], off offset:32
	global_load_dwordx4 v[52:55], v[28:29], off offset:32
	global_load_dwordx4 v[20:23], v[4:5], off offset:64
	global_load_dwordx4 v[56:59], v[28:29], off offset:64
	global_load_dwordx4 v[24:27], v[4:5], off offset:96
	global_load_dwordx4 v[60:63], v[28:29], off offset:96
	v_lshlrev_b32_e32 v92, 1, v84
	v_mov_b32_e32 v93, v65
	s_lshl_b32 s8, s6, 1
	v_mul_u32_u24_e32 v44, s10, v82
	v_lshl_add_u64 v[94:95], s[4:5], 0, v[92:93]
	v_mul_u32_u24_e32 v46, s10, v102
	v_lshlrev_b32_e32 v64, 1, v44
	s_waitcnt vmcnt(0) lgkmcnt(0)
	v_mfma_f32_32x32x16_bf16 v[0:15], v[0:3], v[48:51], 0
	v_mfma_f32_32x32x16_bf16 v[0:15], v[16:19], v[52:55], v[0:15]
	v_lshl_add_u64 v[16:17], v[94:95], 0, s[8:9]
	v_lshl_add_u64 v[28:29], v[16:17], 0, v[64:65]
	v_lshlrev_b32_e32 v64, 1, v46
	v_lshl_add_u64 v[30:31], v[16:17], 0, v[64:65]
	global_load_dwordx2 v[16:17], v[28:29], off
	global_load_dwordx2 v[18:19], v[28:29], off offset:16
	global_load_dwordx2 v[36:37], v[28:29], off offset:32
	global_load_dwordx2 v[38:39], v[28:29], off offset:48
	global_load_dwordx2 v[40:41], v[30:31], off
	global_load_dwordx2 v[42:43], v[30:31], off offset:16
	global_load_dwordx2 v[32:33], v[30:31], off offset:32
	global_load_dwordx2 v[34:35], v[30:31], off offset:48
	v_mfma_f32_32x32x16_bf16 v[0:15], v[20:23], v[56:59], v[0:15]
	v_mfma_f32_32x32x16_bf16 v[0:15], v[24:27], v[60:63], v[0:15]
	s_nop 11
	v_mul_f32_e32 v20, 0x3e000000, v0
	v_mul_f32_e32 v1, 0x3e000000, v1
	v_mul_f32_e32 v21, 0x3e000000, v2
	v_mul_f32_e32 v22, 0x3e000000, v3
	v_mul_f32_e32 v23, 0x3e000000, v4
	v_mul_f32_e32 v5, 0x3e000000, v5
	v_mul_f32_e32 v24, 0x3e000000, v6
	v_mul_f32_e32 v25, 0x3e000000, v7
	v_mul_f32_e32 v26, 0x3e000000, v8
	v_mul_f32_e32 v9, 0x3e000000, v9
	v_mul_f32_e32 v47, 0x3e000000, v12
	v_mul_f32_e64 v12, |v20|, s80
	v_max_f32_e32 v0, 0, v20
	v_min_f32_e32 v64, 0, v20
	v_mul_f32_e64 v20, |v1|, s80
	v_max_f32_e32 v2, 0, v1
	v_min_f32_e32 v74, 0, v1
	v_mul_f32_e64 v28, |v21|, s80
	v_max_f32_e32 v1, 0, v21
	v_min_f32_e32 v75, 0, v21
	v_mul_f32_e64 v21, |v22|, s80
	v_max_f32_e32 v3, 0, v22
	v_min_f32_e32 v76, 0, v22
	v_mul_f32_e64 v22, |v23|, s80
	v_max_f32_e32 v4, 0, v23
	v_min_f32_e32 v77, 0, v23
	v_mul_f32_e64 v23, |v5|, s80
	v_max_f32_e32 v6, 0, v5
	v_min_f32_e32 v78, 0, v5
	v_mul_f32_e64 v29, |v24|, s80
	v_max_f32_e32 v5, 0, v24
	v_min_f32_e32 v79, 0, v24
	v_mul_f32_e64 v24, |v25|, s80
	v_max_f32_e32 v7, 0, v25
	v_min_f32_e32 v80, 0, v25
	v_mul_f32_e64 v25, |v26|, s80
	v_max_f32_e32 v8, 0, v26
	v_min_f32_e32 v81, 0, v26
	v_mul_f32_e64 v26, |v9|, s80
	v_exp_f32_e32 v23, v23
	v_mul_f32_e32 v27, 0x3e000000, v10
	v_mul_f32_e32 v45, 0x3e000000, v11
	v_exp_f32_e32 v26, v26
	v_max_f32_e32 v10, 0, v9
	v_min_f32_e32 v87, 0, v9
	v_mul_f32_e64 v30, |v27|, s80
	v_max_f32_e32 v9, 0, v27
	v_min_f32_e32 v93, 0, v27
	v_mul_f32_e64 v27, |v45|, s80
	v_exp_f32_e32 v24, v24
	v_exp_f32_e32 v27, v27
	v_mul_f32_e64 v31, |v47|, s80
	v_exp_f32_e32 v12, v12
	v_add_f32_e32 v69, 1.0, v23
	v_exp_f32_e32 v20, v20
	v_exp_f32_e32 v21, v21
	v_exp_f32_e32 v66, v31
	v_add_f32_e32 v72, 1.0, v26
	v_log_f32_e32 v26, v69
	v_mul_f32_e32 v69, 0x3e000000, v14
	v_exp_f32_e32 v28, v28
	v_exp_f32_e32 v22, v22
	v_add_f32_e32 v70, 1.0, v24
	v_mul_f32_e64 v14, |v69|, s80
	v_add_f32_e32 v96, 1.0, v27
	v_log_f32_e32 v27, v70
	v_exp_f32_e32 v70, v14
	v_exp_f32_e32 v29, v29
	v_add_f32_e32 v12, 1.0, v12
	v_mul_f32_e32 v13, 0x3e000000, v13
	v_exp_f32_e32 v25, v25
	v_add_f32_e32 v31, 1.0, v20
	v_add_f32_e32 v67, 1.0, v21
	v_log_f32_e32 v20, v12
	v_add_f32_e32 v12, 1.0, v66
	v_mul_f32_e64 v66, |v13|, s80
	v_add_f32_e32 v28, 1.0, v28
	v_add_f32_e32 v68, 1.0, v22
	v_log_f32_e32 v23, v67
	v_exp_f32_e32 v67, v66
	v_exp_f32_e32 v30, v30
	v_log_f32_e32 v22, v31
	v_log_f32_e32 v21, v28
	v_log_f32_e32 v24, v68
	v_log_f32_e32 v31, v96
	v_max_f32_e32 v68, 0, v13
	v_min_f32_e32 v96, 0, v13
	v_add_f32_e32 v13, 1.0, v70
	v_mul_f32_e32 v70, 0x3e000000, v15
	v_add_f32_e32 v29, 1.0, v29
	v_mul_f32_e64 v15, |v70|, s80
	v_add_f32_e32 v71, 1.0, v25
	v_log_f32_e32 v25, v29
	v_exp_f32_e32 v15, v15
	v_add_f32_e32 v67, 1.0, v67
	v_add_f32_e32 v73, 1.0, v30
	v_log_f32_e32 v28, v71
	v_log_f32_e32 v14, v67
	v_max_f32_e32 v67, 0, v69
	v_min_f32_e32 v97, 0, v69
	v_max_f32_e32 v69, 0, v70
	v_min_f32_e32 v98, 0, v70
	v_pk_mul_f32 v[70:71], v[20:21], s[2:3] op_sel_hi:[1,0]
	v_log_f32_e32 v30, v72
	v_log_f32_e32 v29, v73
	v_sub_f32_e32 v64, v64, v70
	v_pk_mul_f32 v[72:73], v[22:23], s[2:3] op_sel_hi:[1,0]
	v_pk_fma_f32 v[0:1], v[20:21], s[2:3], v[0:1] op_sel_hi:[1,0,1]
	v_sub_f32_e32 v20, v75, v71
	v_pk_fma_f32 v[2:3], v[22:23], s[2:3], v[2:3] op_sel_hi:[1,0,1]
	v_add_f32_e32 v15, 1.0, v15
	v_cndmask_b32_e64 v99, v233, v64, s[38:39]
	v_sub_f32_e32 v64, v74, v72
	v_cndmask_b32_e64 v1, 0, v1, s[40:41]
	v_cndmask_b32_e64 v0, 0, v0, s[38:39]
	v_cndmask_b32_e64 v74, v233, v20, s[40:41]
	v_cndmask_b32_e64 v3, 0, v3, s[42:43]
	v_cndmask_b32_e64 v2, 0, v2, s[44:45]
	v_sub_f32_e32 v20, v76, v73
	v_pk_mul_f32 v[22:23], v[24:25], s[2:3] op_sel_hi:[1,0]
	v_pk_mul_f32 v[70:71], v[26:27], s[2:3] op_sel_hi:[1,0]
	v_log_f32_e32 v12, v12
	v_log_f32_e32 v13, v13
; DI void sb_attention(const Params& p, int gw, int NGW, int lane) {
;     ...
;             for (int d0 = 0; d0 < 4; ++d0) { const bf16x8 kf = *(const bf16x8*)(Kb + (size_t)(key0 + n31) * D + d0 * 16 + hi * 8); c = MFMA32(kf, qf[d0], c); }
;     ...
;             float sp[16], ls[16];
; #pragma unroll
;             for (int e = 0; e < 16; ++e) {
;                 const float z = c[e] * 0.125f; const float az = fabsf(z);
;                 const float l = __builtin_amdgcn_logf(1.f + __builtin_amdgcn_exp2f(-az * 1.4426950408889634f)) * 0.6931471805599453f;
;                 const bool valid = !diag || (crow(e, hi) < n31);
;                 sp[e] = valid ? fmaxf(z, 0.f) + l : 0.f; ls[e] = valid ? fminf(z, 0.f) - l : -1e30f;
;             }
;             float Town[4], Toth[4];
; #pragma unroll
;             for (int g = 0; g < 4; ++g) { Town[g] = (sp[4 * g] + sp[4 * g + 1]) + (sp[4 * g + 2] + sp[4 * g + 3]); Toth[g] = __shfl_xor(Town[g], 32); }
;             float suf = R;
;             float pa[16];
; #pragma unroll
;             for (int g = 3; g >= 0; --g) {
;                 const float base = suf + (hi == 0 ? Toth[g] : 0.f);
;                 const float r3 = base, r2 = r3 + sp[4 * g + 3], r1 = r2 + sp[4 * g + 2], r0 = r1 + sp[4 * g + 1];
;                 pa[4 * g + 3] = __builtin_amdgcn_exp2f((ls[4 * g + 3] - r3) * 1.4426950408889634f);
;                 pa[4 * g + 2] = __builtin_amdgcn_exp2f((ls[4 * g + 2] - r2) * 1.4426950408889634f);
;                 pa[4 * g + 1] = __builtin_amdgcn_exp2f((ls[4 * g + 1] - r1) * 1.4426950408889634f);
;                 pa[4 * g + 0] = __builtin_amdgcn_exp2f((ls[4 * g + 0] - r0) * 1.4426950408889634f);
;                 suf += Town[g] + Toth[g];
;             }
;             R = suf;
; #pragma unroll
;             for (int s2 = 0; s2 < 2; ++s2) {
;                 u32x4 pw; pw.x = pk2(pa[8 * s2], pa[8 * s2 + 1]); pw.y = pk2(pa[8 * s2 + 2], pa[8 * s2 + 3]); pw.z = pk2(pa[8 * s2 + 4], pa[8 * s2 + 5]); pw.w = pk2(pa[8 * s2 + 6], pa[8 * s2 + 7]);
;                 const bf16x8 pb = __builtin_bit_cast(bf16x8, pw);
; #pragma unroll
;                 for (int dblk = 0; dblk < 2; ++dblk) { u32x4 vw; vw.x = vlo[s2][dblk].x; vw.y = vlo[s2][dblk].y; vw.z = vhi[s2][dblk].x; vw.w = vhi[s2][dblk].y;
;                     oacc[dblk] = MFMA32(__builtin_bit_cast(bf16x8, vw), pb, oacc[dblk]); }
;             }
;             if (__all(R > 104.f)) break;
	v_log_f32_e32 v15, v15
	v_cndmask_b32_e64 v73, v233, v20, s[42:43]
	v_pk_add_f32 v[20:21], v[0:1], v[2:3]
	v_sub_f32_e32 v0, v77, v22
	v_sub_f32_e32 v22, v78, v70
	v_cndmask_b32_e64 v70, v233, v22, s[52:53]
	v_pk_fma_f32 v[4:5], v[24:25], s[2:3], v[4:5] op_sel_hi:[1,0,1]
	v_sub_f32_e32 v22, v79, v23
	v_pk_fma_f32 v[6:7], v[26:27], s[2:3], v[6:7] op_sel_hi:[1,0,1]
	v_cndmask_b32_e64 v5, 0, v5, s[46:47]
	v_cndmask_b32_e64 v4, 0, v4, s[48:49]
	v_cndmask_b32_e64 v75, v233, v22, s[46:47]
	v_cndmask_b32_e64 v7, 0, v7, s[50:51]
	v_cndmask_b32_e64 v6, 0, v6, s[52:53]
	v_sub_f32_e32 v22, v80, v71
	v_pk_mul_f32 v[24:25], v[28:29], s[2:3] op_sel_hi:[1,0]
	v_max_f32_e32 v11, 0, v45
	v_min_f32_e32 v45, 0, v45
	v_max_f32_e32 v66, 0, v47
	v_cndmask_b32_e64 v71, v233, v22, s[50:51]
	v_pk_add_f32 v[22:23], v[4:5], v[6:7]
	v_sub_f32_e32 v4, v81, v24
	v_pk_mul_f32 v[26:27], v[30:31], s[2:3] op_sel_hi:[1,0]
	v_cndmask_b32_e64 v76, v233, v4, s[56:57]
	v_sub_f32_e32 v4, v87, v26
	v_pk_fma_f32 v[8:9], v[28:29], s[2:3], v[8:9] op_sel_hi:[1,0,1]
	v_sub_f32_e32 v24, v45, v27
	v_pk_mul_f32 v[26:27], v[12:13], s[2:3] op_sel_hi:[1,0]
	v_pk_mul_f32 v[28:29], v[14:15], s[2:3] op_sel_hi:[1,0]
	v_pk_fma_f32 v[12:13], v[12:13], s[2:3], v[66:67] op_sel_hi:[1,0,1]
	v_pk_fma_f32 v[14:15], v[14:15], s[2:3], v[68:69] op_sel_hi:[1,0,1]
	v_cndmask_b32_e64 v13, 0, v13, s[62:63]
	v_cndmask_b32_e64 v12, 0, v12, s[64:65]
	v_cndmask_b32_e64 v15, 0, v15, s[66:67]
	v_cndmask_b32_e64 v14, 0, v14, s[68:69]
	v_pk_fma_f32 v[10:11], v[30:31], s[2:3], v[10:11] op_sel_hi:[1,0,1]
	v_pk_add_f32 v[30:31], v[12:13], v[14:15]
	v_min_f32_e32 v47, 0, v47
	v_pk_add_f32 v[30:31], v[30:31], v[30:31] op_sel:[0,1] op_sel_hi:[1,0]
	ds_bpermute_b32 v31, v85, v30
	v_cndmask_b32_e64 v9, 0, v9, s[54:55]
	v_cndmask_b32_e64 v8, 0, v8, s[56:57]
	v_cndmask_b32_e64 v11, 0, v11, s[58:59]
	v_cndmask_b32_e64 v10, 0, v10, s[60:61]
	v_cndmask_b32_e64 v77, v233, v4, s[60:61]
	v_sub_f32_e32 v4, v93, v25
	v_cndmask_b32_e64 v45, v233, v24, s[58:59]
	v_pk_add_f32 v[24:25], v[8:9], v[10:11]
	v_sub_f32_e32 v8, v47, v26
	v_sub_f32_e32 v26, v96, v28
	s_waitcnt lgkmcnt(0)
	v_add_f32_e32 v28, 0, v31
	v_sub_f32_e32 v12, v97, v27
	v_cndmask_b32_e64 v28, 0, v28, s[36:37]
	v_cndmask_b32_e64 v12, v233, v12, s[62:63]
	v_add_f32_e32 v15, v15, v28
	v_cndmask_b32_e64 v26, v233, v26, s[68:69]
	v_add_f32_e32 v13, v13, v15
	v_sub_f32_e32 v12, v12, v15
	v_add_f32_e32 v14, v14, v13
	v_mul_f32_e32 v68, 0x3fb8aa3b, v12
	v_sub_f32_e32 v15, v26, v13
	v_mov_b32_e32 v12, v24
	v_mov_b32_e32 v13, v30
	v_mov_b32_e32 v30, v25
	v_pk_add_f32 v[12:13], v[12:13], v[30:31]
	v_cndmask_b32_e64 v72, v233, v64, s[44:45]
	ds_bpermute_b32 v64, v85, v12
	v_cndmask_b32_e64 v8, v233, v8, s[64:65]
	v_sub_f32_e32 v8, v8, v14
	v_mul_f32_e32 v78, 0x3fb8aa3b, v8
	v_mul_f32_e32 v15, 0x3fb8aa3b, v15
	s_waitcnt lgkmcnt(0)
	v_cndmask_b32_e64 v8, 0, v64, s[36:37]
	v_pk_add_f32 v[12:13], v[12:13], v[64:65]
	v_exp_f32_e32 v69, v15
	v_add_f32_e32 v14, v8, v13
	v_add_f32_e32 v15, v11, v14
	v_add_f32_e32 v64, v9, v15
	v_mov_b32_e32 v8, v22
	v_mov_b32_e32 v9, v12
	v_mov_b32_e32 v12, v23
	v_pk_add_f32 v[8:9], v[8:9], v[12:13]
	ds_bpermute_b32 v11, v85, v8
	v_cndmask_b32_e64 v4, v233, v4, s[54:55]
	v_sub_f32_e32 v12, v4, v15
	v_add_f32_e32 v79, v10, v64
	v_sub_f32_e32 v10, v45, v14
	s_waitcnt lgkmcnt(0)
	v_cndmask_b32_e64 v4, 0, v11, s[36:37]
	v_add_f32_e32 v4, v4, v9
	v_add_f32_e32 v7, v7, v4
	v_sub_f32_e32 v4, v71, v4
	v_mul_f32_e32 v4, 0x3fb8aa3b, v4
	v_mul_f32_e32 v10, 0x3fb8aa3b, v10
	v_add_f32_e32 v5, v5, v7
	v_exp_f32_e32 v13, v4
	v_sub_f32_e32 v4, v75, v7
	v_exp_f32_e32 v45, v10
	v_add_f32_e32 v6, v6, v5
	v_mul_f32_e32 v7, 0x3fb8aa3b, v4
	v_sub_f32_e32 v14, v70, v5
	v_mov_b32_e32 v4, v20
	v_mov_b32_e32 v5, v8
	v_mov_b32_e32 v10, v21
	v_pk_add_f32 v[4:5], v[4:5], v[10:11]
	ds_bpermute_b32 v8, v85, v4
	v_cndmask_b32_e64 v0, v233, v0, s[48:49]
	v_sub_f32_e32 v0, v0, v6
	v_mul_f32_e32 v10, 0x3fb8aa3b, v14
	v_mul_f32_e32 v0, 0x3fb8aa3b, v0
	s_waitcnt lgkmcnt(0)
	v_cndmask_b32_e64 v6, 0, v8, s[36:37]
	v_pk_add_f32 v[66:67], v[4:5], v[8:9]
	v_exp_f32_e32 v10, v10
	v_add_f32_e32 v4, v6, v67
	v_add_f32_e32 v3, v3, v4
	v_add_f32_e32 v1, v1, v3
	v_add_f32_e32 v2, v2, v1
	v_sub_f32_e32 v4, v73, v4
	v_sub_f32_e32 v3, v74, v3
	v_sub_f32_e32 v1, v72, v1
	v_sub_f32_e32 v2, v99, v2
	v_mul_f32_e32 v4, 0x3fb8aa3b, v4
	v_mul_f32_e32 v3, 0x3fb8aa3b, v3
	v_mul_f32_e32 v1, 0x3fb8aa3b, v1
	v_mul_f32_e32 v2, 0x3fb8aa3b, v2
	v_exp_f32_e32 v4, v4
	v_exp_f32_e32 v1, v1
	v_exp_f32_e32 v2, v2
	v_exp_f32_e32 v3, v3
	v_exp_f32_e32 v5, v0
	v_exp_f32_e32 v6, v7
	v_sub_f32_e32 v27, v98, v29
	v_cvt_pk_bf16_f32 v0, v2, v1
	v_cvt_pk_bf16_f32 v1, v3, v4
	v_sub_f32_e32 v4, v77, v64
	v_cndmask_b32_e64 v27, v233, v27, s[66:67]
	v_mul_f32_e32 v4, 0x3fb8aa3b, v4
	v_sub_f32_e32 v27, v27, v28
	v_exp_f32_e32 v64, v4
	v_sub_f32_e32 v4, v76, v79
	v_mul_f32_e32 v27, 0x3fb8aa3b, v27
	v_cvt_pk_bf16_f32 v2, v5, v10
	v_cvt_pk_bf16_f32 v3, v6, v13
	v_mul_f32_e32 v4, 0x3fb8aa3b, v4
	v_exp_f32_e32 v47, v27
	s_waitcnt vmcnt(0)
	v_mfma_f32_32x32x16_bf16 v[16:31], v[16:19], v[0:3], 0
	v_mul_f32_e32 v70, 0x3fb8aa3b, v12
	v_exp_f32_e32 v71, v4
	v_add_f32_e32 v101, v66, v67
	v_cmp_lt_f32_e32 vcc, s22, v101
	s_cmp_eq_u64 vcc, exec
	s_cselect_b64 s[4:5], -1, 0
	s_cmp_eq_u32 s7, 0
	v_mfma_f32_32x32x16_bf16 v[0:15], v[40:43], v[0:3], 0
	v_exp_f32_e32 v41, v70
	v_exp_f32_e32 v42, v78
	v_exp_f32_e32 v43, v68
	v_cvt_pk_bf16_f32 v40, v71, v64
	v_cvt_pk_bf16_f32 v41, v41, v45
	v_cvt_pk_bf16_f32 v42, v42, v69
	v_cvt_pk_bf16_f32 v43, v43, v47
	s_cselect_b64 s[10:11], -1, 0
	s_or_b64 s[4:5], s[10:11], s[4:5]
	v_mfma_f32_32x32x16_bf16 v[16:31], v[36:39], v[40:43], v[16:31]
	s_and_b64 vcc, exec, s[4:5]
	v_mfma_f32_32x32x16_bf16 v[0:15], v[32:35], v[40:43], v[0:15]
	s_cbranch_vccnz .LBB0_344
	s_lshl_b32 s4, s7, 5
	s_sub_i32 s8, s4, 32
	v_lshlrev_b32_e32 v96, 1, v44
	v_lshlrev_b32_e32 v98, 1, v46
	v_add_u32_e32 v64, s8, v82
	v_lshlrev_b64 v[160:161], 11, v[64:65]
	v_lshl_add_u64 v[160:161], v[90:91], 0, v[160:161]
	global_load_dwordx4 v[144:147], v[160:161], off
	global_load_dwordx4 v[148:151], v[160:161], off offset:32
	global_load_dwordx4 v[152:155], v[160:161], off offset:64
	global_load_dwordx4 v[156:159], v[160:161], off offset:96
; DI int crow(int r, int hi) { return (r & 3) + 8 * (r >> 2) + 4 * hi; }
; #define MFMA32(a, b, c) __builtin_amdgcn_mfma_f32_32x32x16_bf16((a), (b), (c), 0, 0, 0)
; DI void sb_attention(const Params& p, int gw, int NGW, int lane) {
;     ...
;             const int key0 = kb * 32; const bool diag = (kb == kb_start);
;             f32x16 c;
; #pragma unroll
;             for (int e = 0; e < 16; ++e) c[e] = 0.f;
; #pragma unroll
;             for (int d0 = 0; d0 < 4; ++d0) { const bf16x8 kf = *(const bf16x8*)(Kb + (size_t)(key0 + n31) * D + d0 * 16 + hi * 8); c = MFMA32(kf, qf[d0], c); }
;             u32x2 vlo[2][2], vhi[2][2];
; #pragma unroll
;             for (int s2 = 0; s2 < 2; ++s2)
; #pragma unroll
;                 for (int dblk = 0; dblk < 2; ++dblk) { const bf16_t* vp = VT + (size_t)(dblk * 32 + n31) * Lrow + key0 + 16 * s2 + 4 * hi; vlo[s2][dblk] = *(const u32x2*)vp; vhi[s2][dblk] = *(const u32x2*)(vp + 8); }
;             float sp[16], ls[16];
; #pragma unroll
;             for (int e = 0; e < 16; ++e) {
;                 const float z = c[e] * 0.125f; const float az = fabsf(z);
;                 const float l = __builtin_amdgcn_logf(1.f + __builtin_amdgcn_exp2f(-az * 1.4426950408889634f)) * 0.6931471805599453f;
;                 const bool valid = !diag || (crow(e, hi) < n31);
;                 sp[e] = valid ? fmaxf(z, 0.f) + l : 0.f; ls[e] = valid ? fminf(z, 0.f) - l : -1e30f;
;             }
.LBB0_351:
	v_lshl_add_u64 v[32:33], s[8:9], 1, v[94:95]
	v_mov_b32_e32 v97, v65
	v_mov_b32_e32 v99, v65
	v_lshl_add_u64 v[78:79], v[32:33], 0, v[96:97]
	v_lshl_add_u64 v[108:109], v[32:33], 0, v[98:99]
	s_add_i32 s6, s7, -1
	s_waitcnt vmcnt(0) lgkmcnt(0)
	global_load_dwordx2 v[74:75], v[78:79], off
	v_mfma_f32_32x32x16_bf16 v[32:47], v[144:147], v[48:51], 0
	v_mfma_f32_32x32x16_bf16 v[32:47], v[148:151], v[52:55], v[32:47]
	v_mfma_f32_32x32x16_bf16 v[32:47], v[152:155], v[56:59], v[32:47]
	global_load_dwordx2 v[76:77], v[78:79], off offset:16
	global_load_dwordx2 v[70:71], v[78:79], off offset:32
	global_load_dwordx2 v[72:73], v[78:79], off offset:48
	s_nop 0
	global_load_dwordx2 v[78:79], v[108:109], off
	global_load_dwordx2 v[80:81], v[108:109], off offset:16
	global_load_dwordx2 v[66:67], v[108:109], off offset:32
	global_load_dwordx2 v[68:69], v[108:109], off offset:48
	v_mfma_f32_32x32x16_bf16 v[32:47], v[156:159], v[60:63], v[32:47]
	v_add_co_u32_e32 v160, vcc, 0xffff0000, v160
	s_nop 1
	v_addc_co_u32_e32 v161, vcc, -1, v161, vcc
	global_load_dwordx4 v[144:147], v[160:161], off
	global_load_dwordx4 v[148:151], v[160:161], off offset:32
	global_load_dwordx4 v[152:155], v[160:161], off offset:64
	global_load_dwordx4 v[156:159], v[160:161], off offset:96
	s_nop 11
	v_mul_f32_e32 v32, 0x3e000000, v32
	v_mul_f32_e32 v33, 0x3e000000, v33
	v_mul_f32_e32 v64, 0x3e000000, v34
	v_mul_f32_e32 v87, 0x3e000000, v35
	v_mul_f32_e32 v93, 0x3e000000, v36
	v_mul_f32_e32 v97, 0x3e000000, v37
	v_mul_f32_e32 v99, 0x3e000000, v38
	v_mul_f32_e32 v39, 0x3e000000, v39
	v_mul_f32_e32 v103, 0x3e000000, v40
	v_mul_f32_e32 v41, 0x3e000000, v41
	v_mul_f32_e32 v104, 0x3e000000, v42
	v_mul_f32_e32 v105, 0x3e000000, v43
	v_mul_f32_e32 v106, 0x3e000000, v44
	v_mul_f32_e32 v107, 0x3e000000, v45
	v_mul_f32_e32 v108, 0x3e000000, v46
	v_mul_f32_e32 v109, 0x3e000000, v47
	v_mul_f32_e64 v110, |v32|, s80
	v_mul_f32_e64 v111, |v33|, s80
	v_mul_f32_e64 v112, |v64|, s80
	v_mul_f32_e64 v113, |v87|, s80
	v_mul_f32_e64 v114, |v93|, s80
	v_mul_f32_e64 v115, |v97|, s80
	v_mul_f32_e64 v116, |v99|, s80
	v_mul_f32_e64 v117, |v39|, s80
	v_max_f32_e32 v40, 0, v39
	v_min_f32_e32 v126, 0, v39
	v_mul_f32_e64 v39, |v103|, s80
	v_mul_f32_e64 v118, |v41|, s80
	v_mul_f32_e64 v120, |v104|, s80
	v_max_f32_e32 v44, 0, v104
	v_min_f32_e32 v121, 0, v104
	v_mul_f32_e64 v122, |v105|, s80
	v_mul_f32_e64 v123, |v106|, s80
	v_max_f32_e32 v46, 0, v106
	v_min_f32_e32 v128, 0, v106
	v_mul_f32_e64 v106, |v107|, s80
	v_max_f32_e32 v104, 0, v107
	v_min_f32_e32 v129, 0, v107
	v_mul_f32_e64 v107, |v108|, s80
	v_max_f32_e32 v47, 0, v108
	v_min_f32_e32 v130, 0, v108
	v_mul_f32_e64 v108, |v109|, s80
	v_max_f32_e32 v45, 0, v105
	v_min_f32_e32 v127, 0, v105
	v_max_f32_e32 v105, 0, v109
	v_min_f32_e32 v131, 0, v109
	v_exp_f32_e32 v109, v110
	v_exp_f32_e32 v110, v111
	v_exp_f32_e32 v111, v112
	v_exp_f32_e32 v112, v113
	v_exp_f32_e32 v113, v114
	v_exp_f32_e32 v114, v115
	v_exp_f32_e32 v115, v116
	v_exp_f32_e32 v116, v117
	v_exp_f32_e32 v39, v39
	v_exp_f32_e32 v117, v118
	v_exp_f32_e32 v118, v120
	v_exp_f32_e32 v120, v122
	v_exp_f32_e32 v122, v123
	v_exp_f32_e32 v106, v106
	v_exp_f32_e32 v107, v107
	v_exp_f32_e32 v108, v108
	v_add_f32_e32 v109, 1.0, v109
	v_add_f32_e32 v110, 1.0, v110
	v_add_f32_e32 v111, 1.0, v111
	v_add_f32_e32 v112, 1.0, v112
	v_add_f32_e32 v113, 1.0, v113
	v_add_f32_e32 v114, 1.0, v114
	v_add_f32_e32 v115, 1.0, v115
	v_add_f32_e32 v116, 1.0, v116
	v_add_f32_e32 v39, 1.0, v39
	v_add_f32_e32 v117, 1.0, v117
	v_add_f32_e32 v118, 1.0, v118
	v_add_f32_e32 v120, 1.0, v120
	v_add_f32_e32 v122, 1.0, v122
	v_add_f32_e32 v123, 1.0, v106
	v_add_f32_e32 v124, 1.0, v107
	v_add_f32_e32 v125, 1.0, v108
	v_log_f32_e32 v106, v109
	v_log_f32_e32 v108, v110
	v_log_f32_e32 v107, v111
	v_log_f32_e32 v109, v112
	v_log_f32_e32 v132, v113
	v_log_f32_e32 v133, v114
	v_log_f32_e32 v134, v115
	v_log_f32_e32 v135, v116
	v_log_f32_e32 v110, v39
	v_log_f32_e32 v111, v117
	v_log_f32_e32 v112, v118
	v_log_f32_e32 v113, v120
	v_log_f32_e32 v114, v122
	v_log_f32_e32 v116, v123
	v_log_f32_e32 v115, v124
	v_log_f32_e32 v117, v125
	v_max_f32_e32 v34, 0, v32
	v_max_f32_e32 v36, 0, v33
	v_max_f32_e32 v35, 0, v64
	v_max_f32_e32 v37, 0, v87
	v_max_f32_e32 v42, 0, v103
	v_max_f32_e32 v43, 0, v41
	v_min_f32_e32 v119, 0, v32
	v_min_f32_e32 v64, 0, v64
	v_min_f32_e32 v103, 0, v103
	v_min_f32_e32 v41, 0, v41
	v_pk_mul_f32 v[122:123], v[110:111], s[2:3] op_sel_hi:[1,0]
	v_pk_fma_f32 v[42:43], v[110:111], s[2:3], v[42:43] op_sel_hi:[1,0,1]
	v_pk_mul_f32 v[110:111], v[112:113], s[2:3] op_sel_hi:[1,0]
	v_pk_fma_f32 v[44:45], v[112:113], s[2:3], v[44:45] op_sel_hi:[1,0,1]
	v_pk_mul_f32 v[112:113], v[106:107], s[2:3] op_sel_hi:[1,0]
	v_pk_mul_f32 v[124:125], v[108:109], s[2:3] op_sel_hi:[1,0]
	v_pk_fma_f32 v[34:35], v[106:107], s[2:3], v[34:35] op_sel_hi:[1,0,1]
	v_pk_fma_f32 v[36:37], v[108:109], s[2:3], v[36:37] op_sel_hi:[1,0,1]
	v_pk_mul_f32 v[106:107], v[114:115], s[2:3] op_sel_hi:[1,0]
	v_pk_mul_f32 v[108:109], v[116:117], s[2:3] op_sel_hi:[1,0]
	v_pk_fma_f32 v[46:47], v[114:115], s[2:3], v[46:47] op_sel_hi:[1,0,1]
	v_pk_fma_f32 v[104:105], v[116:117], s[2:3], v[104:105] op_sel_hi:[1,0,1]
	v_sub_f32_e32 v103, v103, v122
	v_sub_f32_e32 v116, v41, v123
	v_sub_f32_e32 v117, v121, v110
	v_sub_f32_e32 v122, v127, v111
	v_sub_f32_e32 v123, v119, v112
	v_sub_f32_e32 v64, v64, v113
	v_pk_add_f32 v[110:111], v[34:35], v[36:37]
	v_pk_add_f32 v[112:113], v[42:43], v[42:43] op_sel_hi:[0,1]
	v_pk_add_f32 v[114:115], v[44:45], v[44:45] op_sel_hi:[0,1]
	v_sub_f32_e32 v34, v128, v106
	v_sub_f32_e32 v42, v129, v108
	v_sub_f32_e32 v108, v130, v107
	v_pk_add_f32 v[106:107], v[46:47], v[104:105]
	v_max_f32_e32 v38, 0, v93
	v_mul_f32_e32 v118, 0x3f317218, v132
	v_pk_add_f32 v[106:107], v[106:107], v[106:107] op_sel:[0,1] op_sel_hi:[1,0]
	v_mov_b32_e32 v39, v113
	v_mov_b32_e32 v119, v115
	v_min_f32_e32 v33, 0, v33
	ds_bpermute_b32 v41, v85, v106
	v_pk_add_f32 v[38:39], v[38:39], v[118:119]
	v_sub_f32_e32 v124, v33, v124
	ds_bpermute_b32 v33, v85, v39
	v_max_f32_e32 v32, 0, v97
	v_max_f32_e32 v100, 0, v99
	v_mul_f32_e32 v120, 0x3f317218, v135
	v_mov_b32_e32 v121, v106
	v_fmac_f32_e32 v32, 0x3f317218, v133
	v_fmac_f32_e32 v100, 0x3f317218, v134
	s_waitcnt lgkmcnt(0)
; DI unsigned pk2(float lo, float hi) { f32x2 v = {lo, hi}; bf16x2_t b = __builtin_convertvector(v, bf16x2_t); return __builtin_bit_cast(unsigned, b); }
; #define MFMA32(a, b, c) __builtin_amdgcn_mfma_f32_32x32x16_bf16((a), (b), (c), 0, 0, 0)
; DI void sb_attention(const Params& p, int gw, int NGW, int lane) {
;     ...
;             float Town[4], Toth[4];
; #pragma unroll
;             for (int g = 0; g < 4; ++g) { Town[g] = (sp[4 * g] + sp[4 * g + 1]) + (sp[4 * g + 2] + sp[4 * g + 3]); Toth[g] = __shfl_xor(Town[g], 32); }
;             float suf = R;
;             float pa[16];
; #pragma unroll
;             for (int g = 3; g >= 0; --g) {
;                 const float base = suf + (hi == 0 ? Toth[g] : 0.f);
;                 const float r3 = base, r2 = r3 + sp[4 * g + 3], r1 = r2 + sp[4 * g + 2], r0 = r1 + sp[4 * g + 1];
;                 pa[4 * g + 3] = __builtin_amdgcn_exp2f((ls[4 * g + 3] - r3) * 1.4426950408889634f);
;                 pa[4 * g + 2] = __builtin_amdgcn_exp2f((ls[4 * g + 2] - r2) * 1.4426950408889634f);
;                 pa[4 * g + 1] = __builtin_amdgcn_exp2f((ls[4 * g + 1] - r1) * 1.4426950408889634f);
;                 pa[4 * g + 0] = __builtin_amdgcn_exp2f((ls[4 * g + 0] - r0) * 1.4426950408889634f);
;                 suf += Town[g] + Toth[g];
;             }
;             R = suf;
; #pragma unroll
;             for (int s2 = 0; s2 < 2; ++s2) {
;                 u32x4 pw; pw.x = pk2(pa[8 * s2], pa[8 * s2 + 1]); pw.y = pk2(pa[8 * s2 + 2], pa[8 * s2 + 3]); pw.z = pk2(pa[8 * s2 + 4], pa[8 * s2 + 5]); pw.w = pk2(pa[8 * s2 + 6], pa[8 * s2 + 7]);
;                 const bf16x8 pb = __builtin_bit_cast(bf16x8, pw);
; #pragma unroll
;                 for (int dblk = 0; dblk < 2; ++dblk) { u32x4 vw; vw.x = vlo[s2][dblk].x; vw.y = vlo[s2][dblk].y; vw.z = vhi[s2][dblk].x; vw.w = vhi[s2][dblk].y;
;                     oacc[dblk] = MFMA32(__builtin_bit_cast(bf16x8, vw), pb, oacc[dblk]); }
;             }
;             if (__all(R > 104.f)) break;
	v_cndmask_b32_e64 v106, 0, v41, s[36:37]
	v_pk_add_f32 v[40:41], v[40:41], v[120:121]
	v_mov_b32_e32 v46, v111
	v_add_f32_e32 v111, v101, v106
	v_pk_add_f32 v[106:107], v[100:101], v[40:41]
	v_pk_add_f32 v[38:39], v[38:39], v[32:33]
	v_add_f32_e32 v41, v105, v111
	v_pk_add_f32 v[38:39], v[38:39], v[106:107]
	v_add_f32_e32 v105, v47, v41
	ds_bpermute_b32 v47, v85, v38
	v_cndmask_b32_e64 v33, 0, v33, s[36:37]
	v_add_f32_e32 v33, v33, v107
	v_sub_f32_e32 v109, v131, v109
	v_add_f32_e32 v45, v45, v33
	v_sub_f32_e32 v101, v109, v111
	v_sub_f32_e32 v33, v122, v33
	v_mov_b32_e32 v111, v38
	v_sub_f32_e32 v42, v42, v105
	v_add_f32_e32 v44, v44, v45
	v_add_f32_e32 v38, v104, v105
	v_mul_f32_e32 v33, 0x3fb8aa3b, v33
	v_mul_f32_e32 v104, 0x3fb8aa3b, v42
	v_add_f32_e32 v106, v43, v44
	s_waitcnt lgkmcnt(0)
	v_pk_add_f32 v[42:43], v[110:111], v[46:47]
	v_sub_f32_e32 v105, v34, v38
	v_exp_f32_e32 v107, v33
	v_cndmask_b32_e64 v33, 0, v47, s[36:37]
	ds_bpermute_b32 v38, v85, v42
	v_min_f32_e32 v99, 0, v99
	v_add_f32_e32 v33, v33, v39
	v_fmac_f32_e32 v99, 0xbf317218, v134
	v_fmac_f32_e32 v126, 0xbf317218, v135
	v_add_f32_e32 v34, v40, v33
	v_sub_f32_e32 v33, v126, v33
	v_add_f32_e32 v40, v100, v34
	v_sub_f32_e32 v34, v99, v34
	v_min_f32_e32 v93, 0, v93
	v_min_f32_e32 v97, 0, v97
	v_mul_f32_e32 v33, 0x3fb8aa3b, v33
	v_mul_f32_e32 v34, 0x3fb8aa3b, v34
	v_fmac_f32_e32 v93, 0xbf317218, v132
	v_fmac_f32_e32 v97, 0xbf317218, v133
	v_add_f32_e32 v32, v32, v40
	v_exp_f32_e32 v33, v33
	v_exp_f32_e32 v34, v34
	s_waitcnt lgkmcnt(0)
	v_cndmask_b32_e64 v46, 0, v38, s[36:37]
	v_pk_add_f32 v[38:39], v[42:43], v[38:39]
	v_sub_f32_e32 v40, v97, v40
	v_sub_f32_e32 v32, v93, v32
	v_add_f32_e32 v42, v46, v39
	v_mul_f32_e32 v40, 0x3fb8aa3b, v40
	v_mul_f32_e32 v32, 0x3fb8aa3b, v32
	v_add_f32_e32 v37, v37, v42
	v_min_f32_e32 v87, 0, v87
	v_exp_f32_e32 v40, v40
	v_exp_f32_e32 v32, v32
	v_add_f32_e32 v43, v35, v37
	v_sub_f32_e32 v87, v87, v125
	v_sub_f32_e32 v37, v64, v37
	v_cvt_pk_bf16_f32 v35, v34, v33
	v_add_f32_e32 v33, v36, v43
	v_sub_f32_e32 v42, v87, v42
	v_mul_f32_e32 v34, 0x3fb8aa3b, v37
	v_sub_f32_e32 v37, v124, v43
	v_sub_f32_e32 v33, v123, v33
	v_mul_f32_e32 v42, 0x3fb8aa3b, v42
	v_mul_f32_e32 v37, 0x3fb8aa3b, v37
	v_mul_f32_e32 v33, 0x3fb8aa3b, v33
	v_exp_f32_e32 v36, v42
	v_exp_f32_e32 v42, v34
	v_cvt_pk_bf16_f32 v34, v32, v40
	v_exp_f32_e32 v32, v37
	v_exp_f32_e32 v37, v33
	v_cvt_pk_bf16_f32 v33, v42, v36
	v_sub_f32_e32 v41, v108, v41
	v_sub_f32_e32 v45, v117, v45
	v_cvt_pk_bf16_f32 v32, v37, v32
	v_sub_f32_e32 v36, v116, v44
	v_sub_f32_e32 v43, v103, v106
	s_waitcnt vmcnt(4)
	v_mfma_f32_32x32x16_bf16 v[16:31], v[74:77], v[32:35], v[16:31]
	v_mul_f32_e32 v101, 0x3fb8aa3b, v101
	v_mul_f32_e32 v41, 0x3fb8aa3b, v41
	v_mul_f32_e32 v45, 0x3fb8aa3b, v45
	v_mul_f32_e32 v40, 0x3fb8aa3b, v105
	v_mul_f32_e32 v36, 0x3fb8aa3b, v36
	v_exp_f32_e32 v101, v101
	v_exp_f32_e32 v41, v41
	v_mfma_f32_32x32x16_bf16 v[0:15], v[78:81], v[32:35], v[0:15]
	v_mul_f32_e32 v33, 0x3fb8aa3b, v43
	v_exp_f32_e32 v37, v104
	v_exp_f32_e32 v42, v45
	v_exp_f32_e32 v40, v40
	v_exp_f32_e32 v32, v36
	v_exp_f32_e32 v36, v33
	v_cvt_pk_bf16_f32 v35, v41, v101
	v_cvt_pk_bf16_f32 v33, v42, v107
	v_cvt_pk_bf16_f32 v34, v40, v37
	v_cvt_pk_bf16_f32 v32, v36, v32
	v_add_f32_e32 v101, v38, v39
	v_cmp_lt_f32_e32 vcc, s22, v101
	v_mfma_f32_32x32x16_bf16 v[16:31], v[70:73], v[32:35], v[16:31]
	s_cmp_lg_u64 vcc, exec
	s_cselect_b64 s[4:5], -1, 0
	s_cmp_gt_u32 s7, 1
	s_cselect_b64 s[10:11], -1, 0
	s_and_b64 s[4:5], s[10:11], s[4:5]
	s_mov_b32 s7, s6
	s_sub_i32 s8, s8, 32
	v_mfma_f32_32x32x16_bf16 v[0:15], v[66:69], v[32:35], v[0:15]
	s_and_b64 vcc, exec, s[4:5]
	s_cbranch_vccnz .LBB0_351
	s_branch .LBB0_344

; #define PG8_BAR __builtin_amdgcn_s_barrier()
; template <class Epi, class Sched>
; DI void gemm_phase(LAS unsigned char* lds, const Gemm g, const Sched& S, const Epi& E, const int tid) {
;     ...
;     for (;;) {
;         const bool has_next = S.next(ui + 1, nxt);
;         const char* nA = has_next ? (const char*)g.A + (size_t)nxt.pm * tstepA + (size_t)nxt.pn * g.acol * 2 + (size_t)nxt.k0 * 256 : cA; const char* nB = has_next ? (const char*)g.Bt + (size_t)nxt.pn * tstepB + (size_t)nxt.k0 * 256 : cB;
;         const int nt = 2 * cur.np;
;         for (int t = 0; t < nt; t += 2) {
;             const bool last = (t == nt - 2);
;             const char* a1 = cA + (size_t)(t + 1) * kstep;
;             const char* a2 = last ? nA : cA + (size_t)(t + 2) * kstep; const char* b2 = last ? nB : cB + (size_t)(t + 2) * kstep;
;             const char* a3 = a2 + kstep; const char* b3 = b2 + kstep;
;             PG8_LDB(B0, 0, 0); PG8_LDB(B1, 0, 1); PG8_SCHED; PG8_LDA(At, 0, 0); PG8_STAGE(PG8_SA(1, 1), a1 + hstepA, voffA);
;             PG8_WAIT_V(8); PG8_WAIT_L(0); PG8_BAR; PG8_MMA(0, 0, At, B0); PG8_MMA(0, 1, At, B1); PG8_BAR; PG8_SCHED;
;             PG8_LDA(At, 0, 1); PG8_STAGE(PG8_SB(0, 0), b2, voffB); PG8_STAGE(PG8_SB(0, 1), b2 + hstepB, voffB); PG8_STAGE(PG8_SA(0, 0), a2, voffA);
;             PG8_WAIT_V(8); PG8_WAIT_L(0); PG8_BAR; PG8_MMA(1, 0, At, B0); PG8_MMA(1, 1, At, B1); PG8_BAR; PG8_SCHED;
;             PG8_LDB(B0, 1, 0); PG8_LDB(B1, 1, 1); PG8_SCHED; PG8_LDA(At, 1, 0); PG8_STAGE(PG8_SA(0, 1), a2 + hstepA, voffA);
;             PG8_WAIT_V(8); PG8_WAIT_L(0); PG8_BAR; PG8_MMA(0, 0, At, B0); PG8_MMA(0, 1, At, B1); PG8_BAR; PG8_SCHED;
;             PG8_LDA(At, 1, 1); PG8_STAGE(PG8_SB(1, 0), b3, voffB); PG8_STAGE(PG8_SB(1, 1), b3 + hstepB, voffB); PG8_STAGE(PG8_SA(1, 0), a3, voffA);
;             PG8_WAIT_V(8); PG8_WAIT_L(0); PG8_BAR; PG8_MMA(1, 0, At, B0); PG8_MMA(1, 1, At, B1); PG8_BAR; PG8_SCHED;
;         }
;         if (wr == 0) PG8_BAR;
;         E(acc, cur, wr, wc, fr, fq);
;         if (!has_next) break;
; #pragma unroll
;         for (int a = 0; a < 2; ++a)
; #pragma unroll
;             for (int b = 0; b < 2; ++b)
; #pragma unroll
;                 for (int m = 0; m < 4; ++m)
; #pragma unroll
;                     for (int n = 0; n < 2; ++n) acc[a][b][m][n] = (f32x4){0.f, 0.f, 0.f, 0.f};
;         cur = nxt; cA = nA; cB = nB; ++ui;
.LBB0_1375:
	s_lshl_b32 s10, s75, 1
	s_add_i32 s11, s10, -2
	s_add_u32 s12, s4, 0x100
	s_addc_u32 s13, s5, 0
	s_add_u32 s0, s6, 0x80
	v_mov_b32_e32 v0, 0
	s_addc_u32 s1, s7, 0
	s_mov_b32 s4, 0
	v_mov_b32_e32 v1, v0
	v_mov_b32_e32 v2, v0
	v_mov_b32_e32 v3, v0
	v_mov_b32_e32 v4, v0
	v_mov_b32_e32 v5, v0
	v_mov_b32_e32 v6, v0
	v_mov_b32_e32 v7, v0
	v_mov_b32_e32 v12, v0
	v_mov_b32_e32 v13, v0
	v_mov_b32_e32 v14, v0
	v_mov_b32_e32 v15, v0
	v_mov_b32_e32 v16, v0
	v_mov_b32_e32 v17, v0
	v_mov_b32_e32 v18, v0
	v_mov_b32_e32 v19, v0
	v_mov_b32_e32 v28, v0
	v_mov_b32_e32 v29, v0
	v_mov_b32_e32 v30, v0
	v_mov_b32_e32 v31, v0
	v_mov_b32_e32 v32, v0
	v_mov_b32_e32 v33, v0
	v_mov_b32_e32 v34, v0
	v_mov_b32_e32 v35, v0
	v_mov_b32_e32 v44, v0
	v_mov_b32_e32 v45, v0
	v_mov_b32_e32 v46, v0
	v_mov_b32_e32 v47, v0
	v_mov_b32_e32 v48, v0
	v_mov_b32_e32 v49, v0
	v_mov_b32_e32 v50, v0
	v_mov_b32_e32 v51, v0
	v_mov_b32_e32 v8, v0
	v_mov_b32_e32 v9, v0
	v_mov_b32_e32 v10, v0
	v_mov_b32_e32 v11, v0
	v_mov_b32_e32 v20, v0
	v_mov_b32_e32 v21, v0
	v_mov_b32_e32 v22, v0
	v_mov_b32_e32 v23, v0
	v_mov_b32_e32 v24, v0
	v_mov_b32_e32 v25, v0
	v_mov_b32_e32 v26, v0
	v_mov_b32_e32 v27, v0
	v_mov_b32_e32 v36, v0
	v_mov_b32_e32 v37, v0
	v_mov_b32_e32 v38, v0
	v_mov_b32_e32 v39, v0
	v_mov_b32_e32 v40, v0
	v_mov_b32_e32 v41, v0
	v_mov_b32_e32 v42, v0
	v_mov_b32_e32 v43, v0
	v_mov_b32_e32 v52, v0
	v_mov_b32_e32 v53, v0
	v_mov_b32_e32 v54, v0
	v_mov_b32_e32 v55, v0
	v_mov_b32_e32 v56, v0
	v_mov_b32_e32 v57, v0
	v_mov_b32_e32 v58, v0
	v_mov_b32_e32 v59, v0
	v_mov_b32_e32 v60, v0
	v_mov_b32_e32 v61, v0
	v_mov_b32_e32 v62, v0
	v_mov_b32_e32 v63, v0
	v_mov_b32_e32 v66, v0
	v_mov_b32_e32 v67, v0
	v_mov_b32_e32 v68, v0
	v_mov_b32_e32 v69, v0
	v_mov_b32_e32 v70, v0
	v_mov_b32_e32 v71, v0
	v_mov_b32_e32 v72, v0
	v_mov_b32_e32 v73, v0
	v_mov_b32_e32 v78, v0
	v_mov_b32_e32 v79, v0
	v_mov_b32_e32 v80, v0
	v_mov_b32_e32 v81, v0
	v_mov_b32_e32 v86, v0
	v_mov_b32_e32 v87, v0
	v_mov_b32_e32 v88, v0
	v_mov_b32_e32 v89, v0
	v_mov_b32_e32 v94, v0
	v_mov_b32_e32 v95, v0
	v_mov_b32_e32 v96, v0
	v_mov_b32_e32 v97, v0
	v_mov_b32_e32 v102, v0
	v_mov_b32_e32 v103, v0
	v_mov_b32_e32 v104, v0
	v_mov_b32_e32 v105, v0
	v_mov_b32_e32 v110, v0
	v_mov_b32_e32 v111, v0
	v_mov_b32_e32 v112, v0
	v_mov_b32_e32 v113, v0
	v_mov_b32_e32 v118, v0
	v_mov_b32_e32 v119, v0
	v_mov_b32_e32 v120, v0
	v_mov_b32_e32 v121, v0
	v_mov_b32_e32 v74, v0
	v_mov_b32_e32 v75, v0
	v_mov_b32_e32 v76, v0
	v_mov_b32_e32 v77, v0
	v_mov_b32_e32 v82, v0
	v_mov_b32_e32 v83, v0
	v_mov_b32_e32 v84, v0
	v_mov_b32_e32 v85, v0
	v_mov_b32_e32 v90, v0
	v_mov_b32_e32 v91, v0
	v_mov_b32_e32 v92, v0
	v_mov_b32_e32 v93, v0
	v_mov_b32_e32 v98, v0
	v_mov_b32_e32 v99, v0
	v_mov_b32_e32 v100, v0
	v_mov_b32_e32 v101, v0
	v_mov_b32_e32 v106, v0
	v_mov_b32_e32 v107, v0
	v_mov_b32_e32 v108, v0
	v_mov_b32_e32 v109, v0
	v_mov_b32_e32 v114, v0
	v_mov_b32_e32 v115, v0
	v_mov_b32_e32 v116, v0
	v_mov_b32_e32 v117, v0
	v_mov_b32_e32 v122, v0
	v_mov_b32_e32 v123, v0
	v_mov_b32_e32 v124, v0
	v_mov_b32_e32 v125, v0
	v_mov_b32_e32 v126, v0
	v_mov_b32_e32 v127, v0
	v_mov_b32_e32 v128, v0
	v_mov_b32_e32 v129, v0
	s_waitcnt vmcnt(0)
.LBB0_1376:
	s_add_i32 s6, s4, 2
	s_add_u32 s7, s0, 0x80
	s_addc_u32 s5, s1, 0
	s_add_i32 s27, 0, 0x10000
	s_cmp_eq_u32 s11, s4
	s_cselect_b32 s5, s35, s5
	s_cselect_b32 s4, s34, s7
	s_cselect_b32 s77, s57, s13
	s_cselect_b32 s76, s56, s12
	s_add_i32 s7, 0, 0x14000
	v_add_u32_e32 v142, s27, v195
	v_add_u32_e32 v158, s7, v195
	ds_read_b128 v[130:133], v142
	ds_read_b128 v[134:137], v142 offset:1024
	ds_read_b128 v[138:141], v142 offset:2048
	ds_read_b128 v[142:145], v142 offset:3072
	ds_read_b128 v[146:149], v158
	ds_read_b128 v[150:153], v158 offset:1024
	ds_read_b128 v[154:157], v158 offset:2048
	ds_read_b128 v[158:161], v158 offset:3072
	v_lshl_add_u64 v[192:193], s[0:1], 0, v[186:187]
	s_add_i32 m0, s60, 0xc000
	ds_read_b128 v[162:165], v198
	ds_read_b128 v[166:169], v198 offset:1024
	ds_read_b128 v[170:173], v198 offset:2048
	ds_read_b128 v[174:177], v198 offset:3072
	ds_read_b128 v[188:191], v198 offset:4096
	ds_read_b128 v[200:203], v198 offset:5120
	ds_read_b128 v[204:207], v198 offset:6144
	ds_read_b128 v[208:211], v198 offset:7168
	global_load_lds_dwordx4 v[192:193], off
	v_lshl_add_u64 v[192:193], s[0:1], 0, v[184:185]
	s_add_i32 m0, s60, 0xe000
	s_nop 0
	global_load_lds_dwordx4 v[192:193], off
	s_waitcnt vmcnt(8)
	s_waitcnt lgkmcnt(0)
	s_barrier
	s_setprio 1
	s_waitcnt lgkmcnt(0)
	v_mfma_f32_16x16x32_bf16 v[126:129], v[130:133], v[162:165], v[126:129]
	v_mfma_f32_16x16x32_bf16 v[122:125], v[138:141], v[162:165], v[122:125]
	v_mfma_f32_16x16x32_bf16 v[114:117], v[130:133], v[170:173], v[114:117]
	v_mfma_f32_16x16x32_bf16 v[106:109], v[138:141], v[170:173], v[106:109]
	v_mfma_f32_16x16x32_bf16 v[98:101], v[130:133], v[188:191], v[98:101]
	v_mfma_f32_16x16x32_bf16 v[90:93], v[138:141], v[188:191], v[90:93]
	v_mfma_f32_16x16x32_bf16 v[82:85], v[130:133], v[204:207], v[82:85]
	v_mfma_f32_16x16x32_bf16 v[74:77], v[138:141], v[204:207], v[74:77]
	v_mfma_f32_16x16x32_bf16 v[126:129], v[134:137], v[166:169], v[126:129]
	v_mfma_f32_16x16x32_bf16 v[122:125], v[142:145], v[166:169], v[122:125]
	v_mfma_f32_16x16x32_bf16 v[114:117], v[134:137], v[174:177], v[114:117]
	v_mfma_f32_16x16x32_bf16 v[106:109], v[142:145], v[174:177], v[106:109]
	v_mfma_f32_16x16x32_bf16 v[98:101], v[134:137], v[200:203], v[98:101]
	v_mfma_f32_16x16x32_bf16 v[90:93], v[142:145], v[200:203], v[90:93]
	v_mfma_f32_16x16x32_bf16 v[82:85], v[134:137], v[208:211], v[82:85]
	v_mfma_f32_16x16x32_bf16 v[74:77], v[142:145], v[208:211], v[74:77]
	s_setprio 0
	s_setprio 1
	v_mfma_f32_16x16x32_bf16 v[118:121], v[146:149], v[162:165], v[118:121]
	v_mfma_f32_16x16x32_bf16 v[110:113], v[154:157], v[162:165], v[110:113]
	v_mfma_f32_16x16x32_bf16 v[102:105], v[146:149], v[170:173], v[102:105]
	v_mfma_f32_16x16x32_bf16 v[94:97], v[154:157], v[170:173], v[94:97]
	v_mfma_f32_16x16x32_bf16 v[86:89], v[146:149], v[188:191], v[86:89]
	v_mfma_f32_16x16x32_bf16 v[78:81], v[154:157], v[188:191], v[78:81]
	v_mfma_f32_16x16x32_bf16 v[70:73], v[146:149], v[204:207], v[70:73]
	v_mfma_f32_16x16x32_bf16 v[66:69], v[154:157], v[204:207], v[66:69]
	v_mfma_f32_16x16x32_bf16 v[118:121], v[150:153], v[166:169], v[118:121]
	v_mfma_f32_16x16x32_bf16 v[110:113], v[158:161], v[166:169], v[110:113]
	v_mfma_f32_16x16x32_bf16 v[102:105], v[150:153], v[174:177], v[102:105]
	v_mfma_f32_16x16x32_bf16 v[94:97], v[158:161], v[174:177], v[94:97]
	v_mfma_f32_16x16x32_bf16 v[86:89], v[150:153], v[200:203], v[86:89]
	v_mfma_f32_16x16x32_bf16 v[78:81], v[158:161], v[200:203], v[78:81]
	v_mfma_f32_16x16x32_bf16 v[70:73], v[150:153], v[208:211], v[70:73]
	v_mfma_f32_16x16x32_bf16 v[66:69], v[158:161], v[208:211], v[66:69]
	s_setprio 0
	s_barrier
; #define PG8_STAGE(bufoff, gbase, voff) do { _Pragma("unroll") for (int _i = 0; _i < 2; ++_i) \
;         __builtin_amdgcn_global_load_lds((const unsigned*)((const char*)(gbase) + (voff)[_i]), (LAS unsigned*)(lds + (bufoff) + ldsw + _i * 8192), 16, 0, 0); } while (0)
; #define PG8_LDA(dst, b, h) do { _Pragma("unroll") for (int m = 0; m < 4; ++m) _Pragma("unroll") for (int k = 0; k < 2; ++k) dst[m][k] = *(const LAS bf16x8*)(lds + PG8_SA(b, h) + aoff + m * 2048 + k * 1024); } while (0)
; #define PG8_LDB(dst, b, h) do { _Pragma("unroll") for (int n = 0; n < 2; ++n) _Pragma("unroll") for (int k = 0; k < 2; ++k) dst[n][k] = *(const LAS bf16x8*)(lds + PG8_SB(b, h) + boff + n * 2048 + k * 1024); } while (0)
; #define PG8_MMA(ai, bj, At, Bt) do { __builtin_amdgcn_s_setprio(1); _Pragma("unroll") for (int m = 0; m < 4; ++m) _Pragma("unroll") for (int n = 0; n < 2; ++n) _Pragma("unroll") for (int k = 0; k < 2; ++k) \
;         acc[ai][bj][m][n] = __builtin_amdgcn_mfma_f32_16x16x32_bf16(Bt[n][k], At[m][k], acc[ai][bj][m][n], 0, 0, 0); __builtin_amdgcn_s_setprio(0); } while (0)
; #define PG8_WAIT_V(n) asm volatile("s_waitcnt vmcnt(" #n ")" ::: "memory")
; #define PG8_WAIT_L(n) asm volatile("s_waitcnt lgkmcnt(" #n ")" ::: "memory")
; #define PG8_BAR __builtin_amdgcn_s_barrier()
; #define PG8_SCHED __builtin_amdgcn_sched_barrier(0)
; template <class Epi, class Sched>
; DI void gemm_phase(LAS unsigned char* lds, const Gemm g, const Sched& S, const Epi& E, const int tid) {
;     ...
;             PG8_LDA(At, 0, 1); PG8_STAGE(PG8_SB(0, 0), b2, voffB); PG8_STAGE(PG8_SB(0, 1), b2 + hstepB, voffB); PG8_STAGE(PG8_SA(0, 0), a2, voffA);
;             PG8_WAIT_V(8); PG8_WAIT_L(0); PG8_BAR; PG8_MMA(1, 0, At, B0); PG8_MMA(1, 1, At, B1); PG8_BAR; PG8_SCHED;
;             PG8_LDB(B0, 1, 0); PG8_LDB(B1, 1, 1); PG8_SCHED; PG8_LDA(At, 1, 0); PG8_STAGE(PG8_SA(0, 1), a2 + hstepA, voffA);
	s_add_i32 s27, s27, s59
	v_lshl_add_u64 v[192:193], s[76:77], 0, v[64:65]
	s_mov_b32 m0, s27
	ds_read_b128 v[162:165], v198 offset:16384
	ds_read_b128 v[166:169], v198 offset:17408
	ds_read_b128 v[170:173], v198 offset:18432
	ds_read_b128 v[174:177], v198 offset:19456
	ds_read_b128 v[188:191], v198 offset:20480
	ds_read_b128 v[200:203], v198 offset:21504
	ds_read_b128 v[204:207], v198 offset:22528
	ds_read_b128 v[208:211], v198 offset:23552
	global_load_lds_dwordx4 v[192:193], off
	s_add_i32 m0, s27, 0x2000
	v_lshl_add_u64 v[212:213], s[76:77], 0, v[182:183]
	s_add_u32 s76, s76, s18
	s_addc_u32 s77, s77, 0
	s_add_i32 s7, s7, s59
	global_load_lds_dwordx4 v[212:213], off
	v_lshl_add_u64 v[214:215], s[76:77], 0, v[64:65]
	s_mov_b32 m0, s7
	v_lshl_add_u64 v[218:219], s[76:77], 0, v[182:183]
	global_load_lds_dwordx4 v[214:215], off
	s_add_i32 m0, s7, 0x2000
	v_lshl_add_u64 v[220:221], s[4:5], 0, v[178:179]
	global_load_lds_dwordx4 v[218:219], off
	s_mov_b32 m0, s60
	v_lshl_add_u64 v[224:225], s[4:5], 0, v[180:181]
	global_load_lds_dwordx4 v[220:221], off
	s_mov_b32 m0, s61
	s_nop 0
	global_load_lds_dwordx4 v[224:225], off
	s_waitcnt vmcnt(8)
	s_waitcnt lgkmcnt(0)
	s_barrier
	s_setprio 1
	s_waitcnt lgkmcnt(0)
	v_mfma_f32_16x16x32_bf16 v[60:63], v[130:133], v[162:165], v[60:63]
	v_mfma_f32_16x16x32_bf16 v[56:59], v[138:141], v[162:165], v[56:59]
	v_mfma_f32_16x16x32_bf16 v[52:55], v[130:133], v[170:173], v[52:55]
	v_mfma_f32_16x16x32_bf16 v[40:43], v[138:141], v[170:173], v[40:43]
	v_mfma_f32_16x16x32_bf16 v[36:39], v[130:133], v[188:191], v[36:39]
	v_mfma_f32_16x16x32_bf16 v[24:27], v[138:141], v[188:191], v[24:27]
	v_mfma_f32_16x16x32_bf16 v[20:23], v[130:133], v[204:207], v[20:23]
	v_mfma_f32_16x16x32_bf16 v[8:11], v[138:141], v[204:207], v[8:11]
	v_mfma_f32_16x16x32_bf16 v[60:63], v[134:137], v[166:169], v[60:63]
	v_mfma_f32_16x16x32_bf16 v[56:59], v[142:145], v[166:169], v[56:59]
	v_mfma_f32_16x16x32_bf16 v[52:55], v[134:137], v[174:177], v[52:55]
	v_mfma_f32_16x16x32_bf16 v[40:43], v[142:145], v[174:177], v[40:43]
	v_mfma_f32_16x16x32_bf16 v[36:39], v[134:137], v[200:203], v[36:39]
	v_mfma_f32_16x16x32_bf16 v[24:27], v[142:145], v[200:203], v[24:27]
	v_mfma_f32_16x16x32_bf16 v[20:23], v[134:137], v[208:211], v[20:23]
	v_mfma_f32_16x16x32_bf16 v[8:11], v[142:145], v[208:211], v[8:11]
	s_setprio 0
	s_setprio 1
	v_mfma_f32_16x16x32_bf16 v[48:51], v[146:149], v[162:165], v[48:51]
	v_mfma_f32_16x16x32_bf16 v[44:47], v[154:157], v[162:165], v[44:47]
	v_mfma_f32_16x16x32_bf16 v[32:35], v[146:149], v[170:173], v[32:35]
	v_mfma_f32_16x16x32_bf16 v[28:31], v[154:157], v[170:173], v[28:31]
	v_mfma_f32_16x16x32_bf16 v[16:19], v[146:149], v[188:191], v[16:19]
	v_mfma_f32_16x16x32_bf16 v[12:15], v[154:157], v[188:191], v[12:15]
	v_mfma_f32_16x16x32_bf16 v[4:7], v[146:149], v[204:207], v[4:7]
	v_mfma_f32_16x16x32_bf16 v[0:3], v[154:157], v[204:207], v[0:3]
	v_mfma_f32_16x16x32_bf16 v[48:51], v[150:153], v[166:169], v[48:51]
	v_mfma_f32_16x16x32_bf16 v[44:47], v[158:161], v[166:169], v[44:47]
	v_mfma_f32_16x16x32_bf16 v[32:35], v[150:153], v[174:177], v[32:35]
	v_mfma_f32_16x16x32_bf16 v[28:31], v[158:161], v[174:177], v[28:31]
	v_mfma_f32_16x16x32_bf16 v[16:19], v[150:153], v[200:203], v[16:19]
	v_mfma_f32_16x16x32_bf16 v[12:15], v[158:161], v[200:203], v[12:15]
	v_mfma_f32_16x16x32_bf16 v[4:7], v[150:153], v[208:211], v[4:7]
	v_mfma_f32_16x16x32_bf16 v[0:3], v[158:161], v[208:211], v[0:3]
	s_setprio 0
	s_barrier
	s_add_i32 s7, 0, 0x18000
	s_add_i32 s27, 0, 0x1c000
	v_add_u32_e32 v142, s7, v195
	v_add_u32_e32 v158, s27, v195
	ds_read_b128 v[130:133], v142
	ds_read_b128 v[134:137], v142 offset:1024
	ds_read_b128 v[138:141], v142 offset:2048
	ds_read_b128 v[142:145], v142 offset:3072
	ds_read_b128 v[146:149], v158
	ds_read_b128 v[150:153], v158 offset:1024
	ds_read_b128 v[154:157], v158 offset:2048
	ds_read_b128 v[158:161], v158 offset:3072
	s_add_u32 s4, s4, s8
	s_addc_u32 s5, s5, 0
	s_mov_b32 m0, s62
	v_lshl_add_u64 v[226:227], s[4:5], 0, v[178:179]
	ds_read_b128 v[162:165], v198 offset:32768
	ds_read_b128 v[166:169], v198 offset:33792
	ds_read_b128 v[170:173], v198 offset:34816
	ds_read_b128 v[174:177], v198 offset:35840
	ds_read_b128 v[188:191], v198 offset:36864
	ds_read_b128 v[200:203], v198 offset:37888
	ds_read_b128 v[204:207], v198 offset:38912
	ds_read_b128 v[208:211], v198 offset:39936
	global_load_lds_dwordx4 v[226:227], off
	v_lshl_add_u64 v[226:227], s[4:5], 0, v[180:181]
	s_mov_b32 m0, s63
	s_nop 0
	global_load_lds_dwordx4 v[226:227], off
	s_waitcnt vmcnt(8)
	s_waitcnt lgkmcnt(0)
	s_barrier
; #define PG8_STAGE(bufoff, gbase, voff) do { _Pragma("unroll") for (int _i = 0; _i < 2; ++_i) \
;         __builtin_amdgcn_global_load_lds((const unsigned*)((const char*)(gbase) + (voff)[_i]), (LAS unsigned*)(lds + (bufoff) + ldsw + _i * 8192), 16, 0, 0); } while (0)
; #define PG8_LDA(dst, b, h) do { _Pragma("unroll") for (int m = 0; m < 4; ++m) _Pragma("unroll") for (int k = 0; k < 2; ++k) dst[m][k] = *(const LAS bf16x8*)(lds + PG8_SA(b, h) + aoff + m * 2048 + k * 1024); } while (0)
; #define PG8_MMA(ai, bj, At, Bt) do { __builtin_amdgcn_s_setprio(1); _Pragma("unroll") for (int m = 0; m < 4; ++m) _Pragma("unroll") for (int n = 0; n < 2; ++n) _Pragma("unroll") for (int k = 0; k < 2; ++k) \
;         acc[ai][bj][m][n] = __builtin_amdgcn_mfma_f32_16x16x32_bf16(Bt[n][k], At[m][k], acc[ai][bj][m][n], 0, 0, 0); __builtin_amdgcn_s_setprio(0); } while (0)
; #define PG8_WAIT_V(n) asm volatile("s_waitcnt vmcnt(" #n ")" ::: "memory")
; #define PG8_WAIT_L(n) asm volatile("s_waitcnt lgkmcnt(" #n ")" ::: "memory")
; #define PG8_BAR __builtin_amdgcn_s_barrier()
; #define PG8_SCHED __builtin_amdgcn_sched_barrier(0)
; template <class Epi, class Sched>
; DI void gemm_phase(LAS unsigned char* lds, const Gemm g, const Sched& S, const Epi& E, const int tid) {
;     ...
;             PG8_WAIT_V(8); PG8_WAIT_L(0); PG8_BAR; PG8_MMA(0, 0, At, B0); PG8_MMA(0, 1, At, B1); PG8_BAR; PG8_SCHED;
;             PG8_LDA(At, 1, 1); PG8_STAGE(PG8_SB(1, 0), b3, voffB); PG8_STAGE(PG8_SB(1, 1), b3 + hstepB, voffB); PG8_STAGE(PG8_SA(1, 0), a3, voffA);
;             PG8_WAIT_V(8); PG8_WAIT_L(0); PG8_BAR; PG8_MMA(1, 0, At, B0); PG8_MMA(1, 1, At, B1); PG8_BAR; PG8_SCHED;
;         }
;         if (wr == 0) PG8_BAR;
	s_setprio 1
	s_waitcnt lgkmcnt(0)
	v_mfma_f32_16x16x32_bf16 v[126:129], v[130:133], v[162:165], v[126:129]
	v_mfma_f32_16x16x32_bf16 v[122:125], v[138:141], v[162:165], v[122:125]
	v_mfma_f32_16x16x32_bf16 v[114:117], v[130:133], v[170:173], v[114:117]
	v_mfma_f32_16x16x32_bf16 v[106:109], v[138:141], v[170:173], v[106:109]
	v_mfma_f32_16x16x32_bf16 v[98:101], v[130:133], v[188:191], v[98:101]
	v_mfma_f32_16x16x32_bf16 v[90:93], v[138:141], v[188:191], v[90:93]
	v_mfma_f32_16x16x32_bf16 v[82:85], v[130:133], v[204:207], v[82:85]
	v_mfma_f32_16x16x32_bf16 v[74:77], v[138:141], v[204:207], v[74:77]
	v_mfma_f32_16x16x32_bf16 v[126:129], v[134:137], v[166:169], v[126:129]
	v_mfma_f32_16x16x32_bf16 v[122:125], v[142:145], v[166:169], v[122:125]
	v_mfma_f32_16x16x32_bf16 v[114:117], v[134:137], v[174:177], v[114:117]
	v_mfma_f32_16x16x32_bf16 v[106:109], v[142:145], v[174:177], v[106:109]
	v_mfma_f32_16x16x32_bf16 v[98:101], v[134:137], v[200:203], v[98:101]
	v_mfma_f32_16x16x32_bf16 v[90:93], v[142:145], v[200:203], v[90:93]
	v_mfma_f32_16x16x32_bf16 v[82:85], v[134:137], v[208:211], v[82:85]
	v_mfma_f32_16x16x32_bf16 v[74:77], v[142:145], v[208:211], v[74:77]
	s_setprio 0
	s_setprio 1
	v_mfma_f32_16x16x32_bf16 v[118:121], v[146:149], v[162:165], v[118:121]
	v_mfma_f32_16x16x32_bf16 v[110:113], v[154:157], v[162:165], v[110:113]
	v_mfma_f32_16x16x32_bf16 v[102:105], v[146:149], v[170:173], v[102:105]
	v_mfma_f32_16x16x32_bf16 v[94:97], v[154:157], v[170:173], v[94:97]
	v_mfma_f32_16x16x32_bf16 v[86:89], v[146:149], v[188:191], v[86:89]
	v_mfma_f32_16x16x32_bf16 v[78:81], v[154:157], v[188:191], v[78:81]
	v_mfma_f32_16x16x32_bf16 v[70:73], v[146:149], v[204:207], v[70:73]
	v_mfma_f32_16x16x32_bf16 v[66:69], v[154:157], v[204:207], v[66:69]
	v_mfma_f32_16x16x32_bf16 v[118:121], v[150:153], v[166:169], v[118:121]
	v_mfma_f32_16x16x32_bf16 v[110:113], v[158:161], v[166:169], v[110:113]
	v_mfma_f32_16x16x32_bf16 v[102:105], v[150:153], v[174:177], v[102:105]
	v_mfma_f32_16x16x32_bf16 v[94:97], v[158:161], v[174:177], v[94:97]
	v_mfma_f32_16x16x32_bf16 v[86:89], v[150:153], v[200:203], v[86:89]
	v_mfma_f32_16x16x32_bf16 v[78:81], v[158:161], v[200:203], v[78:81]
	v_mfma_f32_16x16x32_bf16 v[70:73], v[150:153], v[208:211], v[70:73]
	v_mfma_f32_16x16x32_bf16 v[66:69], v[158:161], v[208:211], v[66:69]
	s_setprio 0
	s_barrier
	s_add_i32 s4, s7, s59
	v_lshl_add_u64 v[192:193], v[192:193], 0, s[24:25]
	s_mov_b32 m0, s4
	ds_read_b128 v[162:165], v198 offset:49152
	ds_read_b128 v[166:169], v198 offset:50176
	ds_read_b128 v[170:173], v198 offset:51200
	ds_read_b128 v[174:177], v198 offset:52224
	ds_read_b128 v[188:191], v198 offset:53248
	ds_read_b128 v[200:203], v198 offset:54272
	ds_read_b128 v[204:207], v198 offset:55296
	ds_read_b128 v[208:211], v198 offset:56320
	global_load_lds_dwordx4 v[192:193], off
	v_lshl_add_u64 v[192:193], v[212:213], 0, s[24:25]
	s_add_i32 m0, s4, 0x2000
	s_add_i32 s4, s27, s59
	global_load_lds_dwordx4 v[192:193], off
	v_lshl_add_u64 v[192:193], v[214:215], 0, s[24:25]
	s_mov_b32 m0, s4
	s_nop 0
	global_load_lds_dwordx4 v[192:193], off
	v_lshl_add_u64 v[192:193], v[218:219], 0, s[24:25]
	s_add_i32 m0, s4, 0x2000
	s_nop 0
	global_load_lds_dwordx4 v[192:193], off
	v_lshl_add_u64 v[192:193], v[220:221], 0, s[24:25]
	s_mov_b32 m0, s66
	s_nop 0
	global_load_lds_dwordx4 v[192:193], off
	v_lshl_add_u64 v[192:193], v[224:225], 0, s[24:25]
	s_mov_b32 m0, s67
	s_nop 0
	global_load_lds_dwordx4 v[192:193], off
	s_waitcnt vmcnt(8)
	s_waitcnt lgkmcnt(0)
	s_barrier
	s_setprio 1
	s_waitcnt lgkmcnt(0)
	v_mfma_f32_16x16x32_bf16 v[60:63], v[130:133], v[162:165], v[60:63]
	v_mfma_f32_16x16x32_bf16 v[56:59], v[138:141], v[162:165], v[56:59]
	v_mfma_f32_16x16x32_bf16 v[52:55], v[130:133], v[170:173], v[52:55]
	v_mfma_f32_16x16x32_bf16 v[40:43], v[138:141], v[170:173], v[40:43]
	v_mfma_f32_16x16x32_bf16 v[36:39], v[130:133], v[188:191], v[36:39]
	v_mfma_f32_16x16x32_bf16 v[24:27], v[138:141], v[188:191], v[24:27]
	v_mfma_f32_16x16x32_bf16 v[20:23], v[130:133], v[204:207], v[20:23]
	v_mfma_f32_16x16x32_bf16 v[8:11], v[138:141], v[204:207], v[8:11]
	v_mfma_f32_16x16x32_bf16 v[60:63], v[134:137], v[166:169], v[60:63]
	v_mfma_f32_16x16x32_bf16 v[56:59], v[142:145], v[166:169], v[56:59]
	v_mfma_f32_16x16x32_bf16 v[52:55], v[134:137], v[174:177], v[52:55]
	v_mfma_f32_16x16x32_bf16 v[40:43], v[142:145], v[174:177], v[40:43]
	v_mfma_f32_16x16x32_bf16 v[36:39], v[134:137], v[200:203], v[36:39]
	v_mfma_f32_16x16x32_bf16 v[24:27], v[142:145], v[200:203], v[24:27]
	v_mfma_f32_16x16x32_bf16 v[20:23], v[134:137], v[208:211], v[20:23]
	v_mfma_f32_16x16x32_bf16 v[8:11], v[142:145], v[208:211], v[8:11]
	s_setprio 0
	s_setprio 1
	v_mfma_f32_16x16x32_bf16 v[48:51], v[146:149], v[162:165], v[48:51]
	v_mfma_f32_16x16x32_bf16 v[44:47], v[154:157], v[162:165], v[44:47]
	v_mfma_f32_16x16x32_bf16 v[32:35], v[146:149], v[170:173], v[32:35]
	v_mfma_f32_16x16x32_bf16 v[28:31], v[154:157], v[170:173], v[28:31]
	v_mfma_f32_16x16x32_bf16 v[16:19], v[146:149], v[188:191], v[16:19]
	v_mfma_f32_16x16x32_bf16 v[12:15], v[154:157], v[188:191], v[12:15]
	v_mfma_f32_16x16x32_bf16 v[4:7], v[146:149], v[204:207], v[4:7]
	v_mfma_f32_16x16x32_bf16 v[0:3], v[154:157], v[204:207], v[0:3]
	v_mfma_f32_16x16x32_bf16 v[48:51], v[150:153], v[166:169], v[48:51]
	v_mfma_f32_16x16x32_bf16 v[44:47], v[158:161], v[166:169], v[44:47]
	v_mfma_f32_16x16x32_bf16 v[32:35], v[150:153], v[174:177], v[32:35]
	v_mfma_f32_16x16x32_bf16 v[28:31], v[158:161], v[174:177], v[28:31]
	v_mfma_f32_16x16x32_bf16 v[16:19], v[150:153], v[200:203], v[16:19]
	v_mfma_f32_16x16x32_bf16 v[12:15], v[158:161], v[200:203], v[12:15]
	v_mfma_f32_16x16x32_bf16 v[4:7], v[150:153], v[208:211], v[4:7]
	v_mfma_f32_16x16x32_bf16 v[0:3], v[158:161], v[208:211], v[0:3]
	s_setprio 0
	s_barrier
	s_add_u32 s12, s12, 0x100
	s_addc_u32 s13, s13, 0
	s_add_u32 s0, s0, 0x100
	s_addc_u32 s1, s1, 0
	s_cmp_ge_i32 s6, s10
	s_mov_b32 s4, s6
	s_cbranch_scc0 .LBB0_1376
	s_and_b64 vcc, exec, s[50:51]
	s_cbranch_vccz .LBB0_1379
	s_barrier
